# scan loader: next job's parameter vectors prefetched right after scan_finish (no exposed wait for sample jobs)
# baseline (speedup 1.0000x reference)
; __device__ __forceinline__ f32x4 cv_bf4(const u32x2 w) { return (f32x4){bflo(w.x), bfhi(w.x), bflo(w.y), bfhi(w.y)}; }
; __device__ __forceinline__ void scan_finish(const ScanPtrs& Q, int J, int ci, unsigned char* buf, int ltid, const LStage& L, int toff) {
;     ...
;         const float* mu = Q.mu + gc;
;         r = r + (rp - r) * *(const f32x4*)mu; k0 = k0 + (kp - k0) * *(const f32x4*)(mu + 512); v = v + (vp - v) * *(const f32x4*)(mu + 1024);
;         const f32x4 kk = k0 * *(const f32x4*)(Q.k_k + gc);
;         const float ss = allsum16((kk[0] * kk[0] + kk[1] * kk[1]) + (kk[2] * kk[2] + kk[3] * kk[3]));
;         const float inv = 1.0f / fmaxf(sqrtf(ss), 1e-12f);
;         const f32x4 kkn = kk * inv;
;         const f32x4 dw = cv_bf4(L.sw) + *(const f32x4*)(Q.decay0 + gc);
;         const f32x4 da = cv_bf4(L.sa) + *(const f32x4*)(Q.a0 + gc);
.LBB0_488:
	s_or_b64 exec, exec, s[18:19]
	v_lshl_or_b32 v18, v91, 8, v100
	v_readfirstlane_b32 s99, v91
	s_nop 3
	s_cmp_eq_u32 s99, s98
	s_cbranch_scc1 .Lprm_ok_0
	s_or_b32 s100, s99, 0x100
	s_cmp_eq_u32 s100, s98
	s_cbranch_scc0 .Lprm_ld_0
	s_waitcnt vmcnt(0)
	s_mov_b32 s98, s99
	s_branch .Lprm_ok_0
.Lprm_ld_0:
	s_mov_b32 s98, s99
	s_lshl_b32 s99, s99, 8
	s_mov_b64 s[100:101], exec
	s_mov_b64 exec, -1
	v_or_b32_e32 v229, s99, v100
	global_load_dwordx4 v[186:189], v229, s[30:31] offset:2048
	global_load_dwordx4 v[190:193], v229, s[40:41]
	global_load_dwordx4 v[194:197], v229, s[56:57]
	global_load_dwordx4 v[198:201], v229, s[34:35]
	global_load_dwordx4 v[202:205], v229, s[30:31]
	global_load_dwordx4 v[206:209], v229, s[36:37]
	global_load_dwordx4 v[210:213], v229, s[38:39]
	v_add_u32_e32 v228, 0x1000, v229
	global_load_dwordx4 v[214:217], v228, s[30:31]
	s_waitcnt vmcnt(0)
	s_mov_b64 exec, s[100:101]

; #define SC_ADV(J_, c_) do { if ((J_) < NJOBS) { if (++(c_) >= ((J_) < 256 ? SEQ / SC_CH : 1)) { (J_) += G; (c_) = 0; } } } while (0)
; __device__ void phase_scan(int l, unsigned char* lds) {
;     ...
;             if (Jg < NJOBS) { scan_finish(Q, Jg, cg_, lds + ((it + 2) % 3) * SC_BUFB, tid - 256, L, 0); scan_finish(Q, Jg, cg_, lds + ((it + 2) % 3) * SC_BUFB, tid - 256, L2, 16); }
;             SC_ADV(Jg, cg_);
;             if (Ji < NJOBS) { scan_issue(Q, Ji, cis, tid - 256, L, 0); scan_issue(Q, Ji, cis, tid - 256, L2, 16); }
;             SC_ADV(Ji, cis);
.LBB0_501:
	s_or_b64 exec, exec, s[72:73]
	v_bfe_u32 v228, v94, 2, 3
	s_nop 0
	v_readfirstlane_b32 s99, v228
	s_nop 3
	s_and_b32 s100, s98, 0xff
	s_cmp_eq_u32 s99, s100
	s_cbranch_scc1 .Lprm_nx_0
	s_or_b32 s98, s99, 0x100
	s_lshl_b32 s99, s99, 8
	v_or_b32_e32 v229, s99, v100
	global_load_dwordx4 v[186:189], v229, s[30:31] offset:2048
	global_load_dwordx4 v[190:193], v229, s[40:41]
	global_load_dwordx4 v[194:197], v229, s[56:57]
	global_load_dwordx4 v[198:201], v229, s[34:35]
	global_load_dwordx4 v[202:205], v229, s[30:31]
	global_load_dwordx4 v[206:209], v229, s[36:37]
	global_load_dwordx4 v[210:213], v229, s[38:39]
	v_add_u32_e32 v228, 0x1000, v229
	global_load_dwordx4 v[214:217], v228, s[30:31]
.Lprm_nx_0:
	v_cmp_gt_i32_e32 vcc, s77, v1
	s_and_saveexec_b64 s[20:21], vcc
	s_cbranch_execz .LBB0_521
	v_cmp_lt_i32_e32 vcc, s53, v1
	v_cmp_gt_i32_e64 s[16:17], s76, v1
	s_and_saveexec_b64 s[6:7], s[16:17]
	s_xor_b64 s[18:19], exec, s[6:7]
	s_cbranch_execz .LBB0_512
	v_ashrrev_i32_e32 v21, 5, v1
	v_lshlrev_b32_e32 v18, 5, v0
	v_lshl_add_u32 v18, v21, 11, v18
	s_or_saveexec_b64 s[18:19], s[18:19]
	v_mov_b32_e32 v20, 32
	s_xor_b64 exec, exec, s[18:19]
	s_cbranch_execnz .LBB0_513

; __device__ __forceinline__ f32x4 cv_bf4(const u32x2 w) { return (f32x4){bflo(w.x), bfhi(w.x), bflo(w.y), bfhi(w.y)}; }
; __device__ __forceinline__ void scan_finish(const ScanPtrs& Q, int J, int ci, unsigned char* buf, int ltid, const LStage& L, int toff) {
;     ...
;         const float* mu = Q.mu + gc;
;         r = r + (rp - r) * *(const f32x4*)mu; k0 = k0 + (kp - k0) * *(const f32x4*)(mu + 512); v = v + (vp - v) * *(const f32x4*)(mu + 1024);
;         const f32x4 kk = k0 * *(const f32x4*)(Q.k_k + gc);
;         const float ss = allsum16((kk[0] * kk[0] + kk[1] * kk[1]) + (kk[2] * kk[2] + kk[3] * kk[3]));
;         const float inv = 1.0f / fmaxf(sqrtf(ss), 1e-12f);
;         const f32x4 kkn = kk * inv;
;         const f32x4 dw = cv_bf4(L.sw) + *(const f32x4*)(Q.decay0 + gc);
;         const f32x4 da = cv_bf4(L.sa) + *(const f32x4*)(Q.a0 + gc);
.LBB0_1629:
	s_or_b64 exec, exec, s[16:17]
	v_lshl_or_b32 v18, v91, 8, v100
	v_readfirstlane_b32 s99, v91
	s_nop 3
	s_cmp_eq_u32 s99, s98
	s_cbranch_scc1 .Lprm_ok_1
	s_or_b32 s100, s99, 0x100
	s_cmp_eq_u32 s100, s98
	s_cbranch_scc0 .Lprm_ld_1
	s_waitcnt vmcnt(0)
	s_mov_b32 s98, s99
	s_branch .Lprm_ok_1
.Lprm_ld_1:
	s_mov_b32 s98, s99
	s_lshl_b32 s99, s99, 8
	s_mov_b64 s[100:101], exec
	s_mov_b64 exec, -1
	v_or_b32_e32 v229, s99, v100
	global_load_dwordx4 v[186:189], v229, s[58:59] offset:2048
	global_load_dwordx4 v[190:193], v229, s[34:35] offset:2048
	global_load_dwordx4 v[194:197], v229, s[36:37] offset:2048
	global_load_dwordx4 v[198:201], v229, s[26:27] offset:2048
	global_load_dwordx4 v[202:205], v229, s[58:59]
	global_load_dwordx4 v[206:209], v229, s[28:29] offset:2048
	global_load_dwordx4 v[210:213], v229, s[30:31] offset:2048
	v_add_u32_e32 v228, 0x1000, v229
	global_load_dwordx4 v[214:217], v228, s[58:59]
	s_waitcnt vmcnt(0)
	s_mov_b64 exec, s[100:101]

; #define SC_ADV(J_, c_) do { if ((J_) < NJOBS) { if (++(c_) >= ((J_) < 256 ? SEQ / SC_CH : 1)) { (J_) += G; (c_) = 0; } } } while (0)
; __device__ void phase_scan(int l, unsigned char* lds) {
;     ...
;             if (Jg < NJOBS) { scan_finish(Q, Jg, cg_, lds + ((it + 2) % 3) * SC_BUFB, tid - 256, L, 0); scan_finish(Q, Jg, cg_, lds + ((it + 2) % 3) * SC_BUFB, tid - 256, L2, 16); }
;             SC_ADV(Jg, cg_);
;             if (Ji < NJOBS) { scan_issue(Q, Ji, cis, tid - 256, L, 0); scan_issue(Q, Ji, cis, tid - 256, L2, 16); }
;             SC_ADV(Ji, cis);
.LBB0_1642:
	s_or_b64 exec, exec, s[70:71]
	v_bfe_u32 v228, v94, 2, 3
	s_nop 0
	v_readfirstlane_b32 s99, v228
	s_nop 3
	s_and_b32 s100, s98, 0xff
	s_cmp_eq_u32 s99, s100
	s_cbranch_scc1 .Lprm_nx_1
	s_or_b32 s98, s99, 0x100
	s_lshl_b32 s99, s99, 8
	v_or_b32_e32 v229, s99, v100
	global_load_dwordx4 v[186:189], v229, s[58:59] offset:2048
	global_load_dwordx4 v[190:193], v229, s[34:35] offset:2048
	global_load_dwordx4 v[194:197], v229, s[36:37] offset:2048
	global_load_dwordx4 v[198:201], v229, s[26:27] offset:2048
	global_load_dwordx4 v[202:205], v229, s[58:59]
	global_load_dwordx4 v[206:209], v229, s[28:29] offset:2048
	global_load_dwordx4 v[210:213], v229, s[30:31] offset:2048
	v_add_u32_e32 v228, 0x1000, v229
	global_load_dwordx4 v[214:217], v228, s[58:59]
.Lprm_nx_1:
	v_cmp_gt_i32_e32 vcc, s76, v1
	s_and_saveexec_b64 s[18:19], vcc
	s_cbranch_execz .LBB0_1662
	v_cmp_lt_i32_e32 vcc, s74, v1
	v_cmp_gt_i32_e64 s[14:15], s75, v1
	s_and_saveexec_b64 s[6:7], s[14:15]
	s_xor_b64 s[16:17], exec, s[6:7]
	s_cbranch_execz .LBB0_1653
	v_ashrrev_i32_e32 v21, 5, v1
	v_lshlrev_b32_e32 v18, 5, v0
	v_lshl_add_u32 v18, v21, 11, v18
	s_or_saveexec_b64 s[16:17], s[16:17]
	v_mov_b32_e32 v20, 32
	s_xor_b64 exec, exec, s[16:17]
	s_cbranch_execnz .LBB0_1654
